# st5 epilogue: dedicated path for the GLU gate unit (8 gate loads up front, one wait, stores not waited on; the compiler's path drained the previous block's store in each of 8 row blocks); dead gated b
# speedup vs baseline: 1.0284x; 1.0069x over previous
.LBB0_128:
	s_cmp_lg_u32 s7, 3
	s_cselect_b64 s[22:23], -1, 0
	s_lshl_b32 s8, s10, 1
	v_readlane_b32 s10, v254, 50
	v_lshl_or_b32 v70, s48, 7, v78
	v_readlane_b32 s11, v254, 51
	s_add_u32 s8, s10, s8
	s_addc_u32 s9, s11, 0
	v_ashrrev_i32_e32 v71, 31, v70
	v_lshlrev_b64 v[70:71], 1, v[70:71]
	s_cmp_eq_u32 s7, 4
	v_lshl_add_u64 v[74:75], s[8:9], 0, v[70:71]
	s_cselect_b64 s[8:9], -1, 0
	v_readlane_b32 s10, v255, 0
	s_cmp_eq_u32 s7, 0
	v_readlane_b32 s11, v255, 1
	v_cndmask_b32_e64 v73, 0, 1, s[8:9]
	v_lshl_add_u32 v72, s6, 8, v76
	s_cselect_b64 s[6:7], -1, 0
	v_lshl_add_u64 v[70:71], s[10:11], 0, v[70:71]
	s_mov_b64 s[12:13], -1
	s_and_b64 vcc, exec, s[22:23]
	v_cmp_ne_u32_e64 s[10:11], 1, v73
	s_cbranch_vccz .LBB0_132
	s_and_b64 vcc, exec, s[8:9]
	s_cbranch_vccz .Lbm_fast
	s_branch .Lbm_glu

.LBB0_134:
	v_cndmask_b32_e64 v56, 0, 1, s[22:23]
	v_cmp_ne_u32_e64 s[12:13], 1, v56
	s_andn2_b64 vcc, exec, s[22:23]
	s_mov_b64 s[22:23], -1
	s_cbranch_vccnz .LBB0_138
.LBB0_138:
	s_andn2_b64 vcc, exec, s[22:23]
	s_cbranch_vccnz .LBB0_140

.LBB0_140:
	s_and_b64 vcc, exec, s[12:13]
	s_mov_b64 s[22:23], -1
	s_cbranch_vccnz .LBB0_144
.LBB0_144:
	s_andn2_b64 vcc, exec, s[22:23]
	s_cbranch_vccnz .LBB0_146

.LBB0_146:
	s_and_b64 vcc, exec, s[12:13]
	s_mov_b64 s[22:23], -1
	s_cbranch_vccnz .LBB0_150
.LBB0_150:
	s_andn2_b64 vcc, exec, s[22:23]
	s_cbranch_vccnz .LBB0_152

.LBB0_152:
	s_and_b64 vcc, exec, s[12:13]
	s_mov_b64 s[22:23], -1
	s_cbranch_vccnz .LBB0_156
.LBB0_156:
	s_andn2_b64 vcc, exec, s[22:23]
	s_cbranch_vccnz .LBB0_158

.LBB0_158:
	s_and_b64 vcc, exec, s[12:13]
	s_mov_b64 s[22:23], -1
	s_cbranch_vccnz .LBB0_162
.LBB0_162:
	s_andn2_b64 vcc, exec, s[22:23]
	s_cbranch_vccnz .LBB0_164

.LBB0_164:
	s_and_b64 vcc, exec, s[12:13]
	s_mov_b64 s[22:23], -1
	s_cbranch_vccnz .LBB0_168
.LBB0_168:
	s_andn2_b64 vcc, exec, s[22:23]
	s_cbranch_vccnz .LBB0_170

.LBB0_170:
	s_and_b64 vcc, exec, s[12:13]
	s_mov_b64 s[12:13], -1
	s_cbranch_vccnz .LBB0_175
.LBB0_174:
	s_mov_b64 s[6:7], -1
	s_and_b64 vcc, exec, s[4:5]
	s_cbranch_vccz .LBB0_95
	s_branch .LBB0_177

.Lbm_glu:
	v_mad_i64_i32 v[248:249], s[12:13], v72, s2, v[74:75]
	global_load_dwordx4 v[208:211], v[248:249], off
	v_or_b32_e32 v250, 16, v72
	v_mad_i64_i32 v[248:249], s[12:13], v250, s2, v[74:75]
	global_load_dwordx4 v[212:215], v[248:249], off
	v_or_b32_e32 v250, 32, v72
	v_mad_i64_i32 v[248:249], s[12:13], v250, s2, v[74:75]
	global_load_dwordx4 v[216:219], v[248:249], off
	v_or_b32_e32 v250, 48, v72
	v_mad_i64_i32 v[248:249], s[12:13], v250, s2, v[74:75]
	global_load_dwordx4 v[220:223], v[248:249], off
	v_add_u32_e32 v250, 0x80, v72
	v_mad_i64_i32 v[248:249], s[12:13], v250, s2, v[74:75]
	global_load_dwordx4 v[224:227], v[248:249], off
	v_add_u32_e32 v250, 0x90, v72
	v_mad_i64_i32 v[248:249], s[12:13], v250, s2, v[74:75]
	global_load_dwordx4 v[228:231], v[248:249], off
	v_add_u32_e32 v250, 0xa0, v72
	v_mad_i64_i32 v[248:249], s[12:13], v250, s2, v[74:75]
	global_load_dwordx4 v[232:235], v[248:249], off
	v_add_u32_e32 v250, 0xb0, v72
	v_mad_i64_i32 v[248:249], s[12:13], v250, s2, v[74:75]
	global_load_dwordx4 v[240:243], v[248:249], off
	v_mul_f32_e32 v186, 0xbfb8aa3b, v60
	v_mul_f32_e32 v187, 0xbfb8aa3b, v61
	v_mul_f32_e32 v188, 0xbfb8aa3b, v62
	v_mul_f32_e32 v189, 0xbfb8aa3b, v63
	v_mul_f32_e32 v190, 0xbfb8aa3b, v56
	v_mul_f32_e32 v191, 0xbfb8aa3b, v57
	v_mul_f32_e32 v192, 0xbfb8aa3b, v58
	v_mul_f32_e32 v193, 0xbfb8aa3b, v59
	v_exp_f32_e32 v186, v186
	v_exp_f32_e32 v187, v187
	v_exp_f32_e32 v188, v188
	v_exp_f32_e32 v189, v189
	v_exp_f32_e32 v190, v190
	v_exp_f32_e32 v191, v191
	v_exp_f32_e32 v192, v192
	v_exp_f32_e32 v193, v193
	v_add_f32_e32 v186, 1.0, v186
	v_add_f32_e32 v187, 1.0, v187
	v_add_f32_e32 v188, 1.0, v188
	v_add_f32_e32 v189, 1.0, v189
	v_add_f32_e32 v190, 1.0, v190
	v_add_f32_e32 v191, 1.0, v191
	v_add_f32_e32 v192, 1.0, v192
	v_add_f32_e32 v193, 1.0, v193
	v_rcp_f32_e32 v186, v186
	v_rcp_f32_e32 v187, v187
	v_rcp_f32_e32 v188, v188
	v_rcp_f32_e32 v189, v189
	v_rcp_f32_e32 v190, v190
	v_rcp_f32_e32 v191, v191
	v_rcp_f32_e32 v192, v192
	v_rcp_f32_e32 v193, v193
	v_lshlrev_b32_e32 v60, 16, v108
	v_and_b32_e32 v61, 0xffff0000, v108
	v_lshlrev_b32_e32 v62, 16, v111
	v_and_b32_e32 v63, 0xffff0000, v111
	v_lshlrev_b32_e32 v56, 16, v107
	v_and_b32_e32 v57, 0xffff0000, v107
	v_lshlrev_b32_e32 v58, 16, v110
	v_and_b32_e32 v59, 0xffff0000, v110
	v_mul_f32_e32 v60, v186, v60
	v_mul_f32_e32 v61, v187, v61
	v_mul_f32_e32 v62, v188, v62
	v_mul_f32_e32 v63, v189, v63
	v_mul_f32_e32 v56, v190, v56
	v_mul_f32_e32 v57, v191, v57
	v_mul_f32_e32 v58, v192, v58
	v_mul_f32_e32 v59, v193, v59
	v_mul_f32_e32 v186, 0xbfb8aa3b, v52
	v_mul_f32_e32 v187, 0xbfb8aa3b, v53
	v_mul_f32_e32 v188, 0xbfb8aa3b, v54
	v_mul_f32_e32 v189, 0xbfb8aa3b, v55
	v_mul_f32_e32 v190, 0xbfb8aa3b, v48
	v_mul_f32_e32 v191, 0xbfb8aa3b, v49
	v_mul_f32_e32 v192, 0xbfb8aa3b, v50
	v_mul_f32_e32 v193, 0xbfb8aa3b, v51
	v_exp_f32_e32 v186, v186
	v_exp_f32_e32 v187, v187
	v_exp_f32_e32 v188, v188
	v_exp_f32_e32 v189, v189
	v_exp_f32_e32 v190, v190
	v_exp_f32_e32 v191, v191
	v_exp_f32_e32 v192, v192
	v_exp_f32_e32 v193, v193
	v_add_f32_e32 v186, 1.0, v186
	v_add_f32_e32 v187, 1.0, v187
	v_add_f32_e32 v188, 1.0, v188
	v_add_f32_e32 v189, 1.0, v189
	v_add_f32_e32 v190, 1.0, v190
	v_add_f32_e32 v191, 1.0, v191
	v_add_f32_e32 v192, 1.0, v192
	v_add_f32_e32 v193, 1.0, v193
	v_rcp_f32_e32 v186, v186
	v_rcp_f32_e32 v187, v187
	v_rcp_f32_e32 v188, v188
	v_rcp_f32_e32 v189, v189
	v_rcp_f32_e32 v190, v190
	v_rcp_f32_e32 v191, v191
	v_rcp_f32_e32 v192, v192
	v_rcp_f32_e32 v193, v193
	v_lshlrev_b32_e32 v52, 16, v104
	v_and_b32_e32 v53, 0xffff0000, v104
	v_lshlrev_b32_e32 v54, 16, v106
	v_and_b32_e32 v55, 0xffff0000, v106
	v_lshlrev_b32_e32 v48, 16, v103
	v_and_b32_e32 v49, 0xffff0000, v103
	v_lshlrev_b32_e32 v50, 16, v105
	v_and_b32_e32 v51, 0xffff0000, v105
	v_mul_f32_e32 v52, v186, v52
	v_mul_f32_e32 v53, v187, v53
	v_mul_f32_e32 v54, v188, v54
	v_mul_f32_e32 v55, v189, v55
	v_mul_f32_e32 v48, v190, v48
	v_mul_f32_e32 v49, v191, v49
	v_mul_f32_e32 v50, v192, v50
	v_mul_f32_e32 v51, v193, v51
	v_mul_f32_e32 v186, 0xbfb8aa3b, v44
	v_mul_f32_e32 v187, 0xbfb8aa3b, v45
	v_mul_f32_e32 v188, 0xbfb8aa3b, v46
	v_mul_f32_e32 v189, 0xbfb8aa3b, v47
	v_mul_f32_e32 v190, 0xbfb8aa3b, v40
	v_mul_f32_e32 v191, 0xbfb8aa3b, v41
	v_mul_f32_e32 v192, 0xbfb8aa3b, v42
	v_mul_f32_e32 v193, 0xbfb8aa3b, v43
	v_exp_f32_e32 v186, v186
	v_exp_f32_e32 v187, v187
	v_exp_f32_e32 v188, v188
	v_exp_f32_e32 v189, v189
	v_exp_f32_e32 v190, v190
	v_exp_f32_e32 v191, v191
	v_exp_f32_e32 v192, v192
	v_exp_f32_e32 v193, v193
	v_add_f32_e32 v186, 1.0, v186
	v_add_f32_e32 v187, 1.0, v187
	v_add_f32_e32 v188, 1.0, v188
	v_add_f32_e32 v189, 1.0, v189
	v_add_f32_e32 v190, 1.0, v190
	v_add_f32_e32 v191, 1.0, v191
	v_add_f32_e32 v192, 1.0, v192
	v_add_f32_e32 v193, 1.0, v193
	v_rcp_f32_e32 v186, v186
	v_rcp_f32_e32 v187, v187
	v_rcp_f32_e32 v188, v188
	v_rcp_f32_e32 v189, v189
	v_rcp_f32_e32 v190, v190
	v_rcp_f32_e32 v191, v191
	v_rcp_f32_e32 v192, v192
	v_rcp_f32_e32 v193, v193
	v_lshlrev_b32_e32 v44, 16, v100
	v_and_b32_e32 v45, 0xffff0000, v100
	v_lshlrev_b32_e32 v46, 16, v102
	v_and_b32_e32 v47, 0xffff0000, v102
	v_lshlrev_b32_e32 v40, 16, v99
	v_and_b32_e32 v41, 0xffff0000, v99
	v_lshlrev_b32_e32 v42, 16, v101
	v_and_b32_e32 v43, 0xffff0000, v101
	v_mul_f32_e32 v44, v186, v44
	v_mul_f32_e32 v45, v187, v45
	v_mul_f32_e32 v46, v188, v46
	v_mul_f32_e32 v47, v189, v47
	v_mul_f32_e32 v40, v190, v40
	v_mul_f32_e32 v41, v191, v41
	v_mul_f32_e32 v42, v192, v42
	v_mul_f32_e32 v43, v193, v43
	v_mul_f32_e32 v186, 0xbfb8aa3b, v36
	v_mul_f32_e32 v187, 0xbfb8aa3b, v37
	v_mul_f32_e32 v188, 0xbfb8aa3b, v38
	v_mul_f32_e32 v189, 0xbfb8aa3b, v39
	v_mul_f32_e32 v190, 0xbfb8aa3b, v32
	v_mul_f32_e32 v191, 0xbfb8aa3b, v33
	v_mul_f32_e32 v192, 0xbfb8aa3b, v34
	v_mul_f32_e32 v193, 0xbfb8aa3b, v35
	v_exp_f32_e32 v186, v186
	v_exp_f32_e32 v187, v187
	v_exp_f32_e32 v188, v188
	v_exp_f32_e32 v189, v189
	v_exp_f32_e32 v190, v190
	v_exp_f32_e32 v191, v191
	v_exp_f32_e32 v192, v192
	v_exp_f32_e32 v193, v193
	v_add_f32_e32 v186, 1.0, v186
	v_add_f32_e32 v187, 1.0, v187
	v_add_f32_e32 v188, 1.0, v188
	v_add_f32_e32 v189, 1.0, v189
	v_add_f32_e32 v190, 1.0, v190
	v_add_f32_e32 v191, 1.0, v191
	v_add_f32_e32 v192, 1.0, v192
	v_add_f32_e32 v193, 1.0, v193
	v_rcp_f32_e32 v186, v186
	v_rcp_f32_e32 v187, v187
	v_rcp_f32_e32 v188, v188
	v_rcp_f32_e32 v189, v189
	v_rcp_f32_e32 v190, v190
	v_rcp_f32_e32 v191, v191
	v_rcp_f32_e32 v192, v192
	v_rcp_f32_e32 v193, v193
	v_lshlrev_b32_e32 v36, 16, v96
	v_and_b32_e32 v37, 0xffff0000, v96
	v_lshlrev_b32_e32 v38, 16, v98
	v_and_b32_e32 v39, 0xffff0000, v98
	v_lshlrev_b32_e32 v32, 16, v95
	v_and_b32_e32 v33, 0xffff0000, v95
	v_lshlrev_b32_e32 v34, 16, v97
	v_and_b32_e32 v35, 0xffff0000, v97
	v_mul_f32_e32 v36, v186, v36
	v_mul_f32_e32 v37, v187, v37
	v_mul_f32_e32 v38, v188, v38
	v_mul_f32_e32 v39, v189, v39
	v_mul_f32_e32 v32, v190, v32
	v_mul_f32_e32 v33, v191, v33
	v_mul_f32_e32 v34, v192, v34
	v_mul_f32_e32 v35, v193, v35
	v_mul_f32_e32 v186, 0xbfb8aa3b, v28
	v_mul_f32_e32 v187, 0xbfb8aa3b, v29
	v_mul_f32_e32 v188, 0xbfb8aa3b, v30
	v_mul_f32_e32 v189, 0xbfb8aa3b, v31
	v_mul_f32_e32 v190, 0xbfb8aa3b, v24
	v_mul_f32_e32 v191, 0xbfb8aa3b, v25
	v_mul_f32_e32 v192, 0xbfb8aa3b, v26
	v_mul_f32_e32 v193, 0xbfb8aa3b, v27
	v_exp_f32_e32 v186, v186
	v_exp_f32_e32 v187, v187
	v_exp_f32_e32 v188, v188
	v_exp_f32_e32 v189, v189
	v_exp_f32_e32 v190, v190
	v_exp_f32_e32 v191, v191
	v_exp_f32_e32 v192, v192
	v_exp_f32_e32 v193, v193
	v_add_f32_e32 v186, 1.0, v186
	v_add_f32_e32 v187, 1.0, v187
	v_add_f32_e32 v188, 1.0, v188
	v_add_f32_e32 v189, 1.0, v189
	v_add_f32_e32 v190, 1.0, v190
	v_add_f32_e32 v191, 1.0, v191
	v_add_f32_e32 v192, 1.0, v192
	v_add_f32_e32 v193, 1.0, v193
	v_rcp_f32_e32 v186, v186
	v_rcp_f32_e32 v187, v187
	v_rcp_f32_e32 v188, v188
	v_rcp_f32_e32 v189, v189
	v_rcp_f32_e32 v190, v190
	v_rcp_f32_e32 v191, v191
	v_rcp_f32_e32 v192, v192
	v_rcp_f32_e32 v193, v193
	v_lshlrev_b32_e32 v28, 16, v92
	v_and_b32_e32 v29, 0xffff0000, v92
	v_lshlrev_b32_e32 v30, 16, v94
	v_and_b32_e32 v31, 0xffff0000, v94
	v_lshlrev_b32_e32 v24, 16, v91
	v_and_b32_e32 v25, 0xffff0000, v91
	v_lshlrev_b32_e32 v26, 16, v93
	v_and_b32_e32 v27, 0xffff0000, v93
	v_mul_f32_e32 v28, v186, v28
	v_mul_f32_e32 v29, v187, v29
	v_mul_f32_e32 v30, v188, v30
	v_mul_f32_e32 v31, v189, v31
	v_mul_f32_e32 v24, v190, v24
	v_mul_f32_e32 v25, v191, v25
	v_mul_f32_e32 v26, v192, v26
	v_mul_f32_e32 v27, v193, v27
	v_mul_f32_e32 v186, 0xbfb8aa3b, v20
	v_mul_f32_e32 v187, 0xbfb8aa3b, v21
	v_mul_f32_e32 v188, 0xbfb8aa3b, v22
	v_mul_f32_e32 v189, 0xbfb8aa3b, v23
	v_mul_f32_e32 v190, 0xbfb8aa3b, v16
	v_mul_f32_e32 v191, 0xbfb8aa3b, v17
	v_mul_f32_e32 v192, 0xbfb8aa3b, v18
	v_mul_f32_e32 v193, 0xbfb8aa3b, v19
	v_exp_f32_e32 v186, v186
	v_exp_f32_e32 v187, v187
	v_exp_f32_e32 v188, v188
	v_exp_f32_e32 v189, v189
	v_exp_f32_e32 v190, v190
	v_exp_f32_e32 v191, v191
	v_exp_f32_e32 v192, v192
	v_exp_f32_e32 v193, v193
	v_add_f32_e32 v186, 1.0, v186
	v_add_f32_e32 v187, 1.0, v187
	v_add_f32_e32 v188, 1.0, v188
	v_add_f32_e32 v189, 1.0, v189
	v_add_f32_e32 v190, 1.0, v190
	v_add_f32_e32 v191, 1.0, v191
	v_add_f32_e32 v192, 1.0, v192
	v_add_f32_e32 v193, 1.0, v193
	v_rcp_f32_e32 v186, v186
	v_rcp_f32_e32 v187, v187
	v_rcp_f32_e32 v188, v188
	v_rcp_f32_e32 v189, v189
	v_rcp_f32_e32 v190, v190
	v_rcp_f32_e32 v191, v191
	v_rcp_f32_e32 v192, v192
	v_rcp_f32_e32 v193, v193
	v_lshlrev_b32_e32 v20, 16, v88
	v_and_b32_e32 v21, 0xffff0000, v88
	v_lshlrev_b32_e32 v22, 16, v90
	v_and_b32_e32 v23, 0xffff0000, v90
	v_lshlrev_b32_e32 v16, 16, v87
	v_and_b32_e32 v17, 0xffff0000, v87
	v_lshlrev_b32_e32 v18, 16, v89
	v_and_b32_e32 v19, 0xffff0000, v89
	v_mul_f32_e32 v20, v186, v20
	v_mul_f32_e32 v21, v187, v21
	v_mul_f32_e32 v22, v188, v22
	v_mul_f32_e32 v23, v189, v23
	v_mul_f32_e32 v16, v190, v16
	v_mul_f32_e32 v17, v191, v17
	v_mul_f32_e32 v18, v192, v18
	v_mul_f32_e32 v19, v193, v19
	v_mul_f32_e32 v186, 0xbfb8aa3b, v12
	v_mul_f32_e32 v187, 0xbfb8aa3b, v13
	v_mul_f32_e32 v188, 0xbfb8aa3b, v14
	v_mul_f32_e32 v189, 0xbfb8aa3b, v15
	v_mul_f32_e32 v190, 0xbfb8aa3b, v8
	v_mul_f32_e32 v191, 0xbfb8aa3b, v9
	v_mul_f32_e32 v192, 0xbfb8aa3b, v10
	v_mul_f32_e32 v193, 0xbfb8aa3b, v11
	v_exp_f32_e32 v186, v186
	v_exp_f32_e32 v187, v187
	v_exp_f32_e32 v188, v188
	v_exp_f32_e32 v189, v189
	v_exp_f32_e32 v190, v190
	v_exp_f32_e32 v191, v191
	v_exp_f32_e32 v192, v192
	v_exp_f32_e32 v193, v193
	v_add_f32_e32 v186, 1.0, v186
	v_add_f32_e32 v187, 1.0, v187
	v_add_f32_e32 v188, 1.0, v188
	v_add_f32_e32 v189, 1.0, v189
	v_add_f32_e32 v190, 1.0, v190
	v_add_f32_e32 v191, 1.0, v191
	v_add_f32_e32 v192, 1.0, v192
	v_add_f32_e32 v193, 1.0, v193
	v_rcp_f32_e32 v186, v186
	v_rcp_f32_e32 v187, v187
	v_rcp_f32_e32 v188, v188
	v_rcp_f32_e32 v189, v189
	v_rcp_f32_e32 v190, v190
	v_rcp_f32_e32 v191, v191
	v_rcp_f32_e32 v192, v192
	v_rcp_f32_e32 v193, v193
	v_lshlrev_b32_e32 v12, 16, v84
	v_and_b32_e32 v13, 0xffff0000, v84
	v_lshlrev_b32_e32 v14, 16, v86
	v_and_b32_e32 v15, 0xffff0000, v86
	v_lshlrev_b32_e32 v8, 16, v83
	v_and_b32_e32 v9, 0xffff0000, v83
	v_lshlrev_b32_e32 v10, 16, v85
	v_and_b32_e32 v11, 0xffff0000, v85
	v_mul_f32_e32 v12, v186, v12
	v_mul_f32_e32 v13, v187, v13
	v_mul_f32_e32 v14, v188, v14
	v_mul_f32_e32 v15, v189, v15
	v_mul_f32_e32 v8, v190, v8
	v_mul_f32_e32 v9, v191, v9
	v_mul_f32_e32 v10, v192, v10
	v_mul_f32_e32 v11, v193, v11
	v_mul_f32_e32 v186, 0xbfb8aa3b, v4
	v_mul_f32_e32 v187, 0xbfb8aa3b, v5
	v_mul_f32_e32 v188, 0xbfb8aa3b, v6
	v_mul_f32_e32 v189, 0xbfb8aa3b, v7
	v_mul_f32_e32 v190, 0xbfb8aa3b, v0
	v_mul_f32_e32 v191, 0xbfb8aa3b, v1
	v_mul_f32_e32 v192, 0xbfb8aa3b, v2
	v_mul_f32_e32 v193, 0xbfb8aa3b, v3
	v_exp_f32_e32 v186, v186
	v_exp_f32_e32 v187, v187
	v_exp_f32_e32 v188, v188
	v_exp_f32_e32 v189, v189
	v_exp_f32_e32 v190, v190
	v_exp_f32_e32 v191, v191
	v_exp_f32_e32 v192, v192
	v_exp_f32_e32 v193, v193
	v_add_f32_e32 v186, 1.0, v186
	v_add_f32_e32 v187, 1.0, v187
	v_add_f32_e32 v188, 1.0, v188
	v_add_f32_e32 v189, 1.0, v189
	v_add_f32_e32 v190, 1.0, v190
	v_add_f32_e32 v191, 1.0, v191
	v_add_f32_e32 v192, 1.0, v192
	v_add_f32_e32 v193, 1.0, v193
	v_rcp_f32_e32 v186, v186
	v_rcp_f32_e32 v187, v187
	v_rcp_f32_e32 v188, v188
	v_rcp_f32_e32 v189, v189
	v_rcp_f32_e32 v190, v190
	v_rcp_f32_e32 v191, v191
	v_rcp_f32_e32 v192, v192
	v_rcp_f32_e32 v193, v193
	v_lshlrev_b32_e32 v4, 16, v80
	v_and_b32_e32 v5, 0xffff0000, v80
	v_lshlrev_b32_e32 v6, 16, v82
	v_and_b32_e32 v7, 0xffff0000, v82
	v_lshlrev_b32_e32 v0, 16, v79
	v_and_b32_e32 v1, 0xffff0000, v79
	v_lshlrev_b32_e32 v2, 16, v81
	v_and_b32_e32 v3, 0xffff0000, v81
	v_mul_f32_e32 v4, v186, v4
	v_mul_f32_e32 v5, v187, v5
	v_mul_f32_e32 v6, v188, v6
	v_mul_f32_e32 v7, v189, v7
	v_mul_f32_e32 v0, v190, v0
	v_mul_f32_e32 v1, v191, v1
	v_mul_f32_e32 v2, v192, v2
	v_mul_f32_e32 v3, v193, v3
	s_waitcnt vmcnt(0)
	v_lshlrev_b32_e32 v186, 16, v208
	v_and_b32_e32 v187, 0xffff0000, v208
	v_lshlrev_b32_e32 v188, 16, v209
	v_and_b32_e32 v189, 0xffff0000, v209
	v_lshlrev_b32_e32 v190, 16, v210
	v_and_b32_e32 v191, 0xffff0000, v210
	v_lshlrev_b32_e32 v192, 16, v211
	v_and_b32_e32 v193, 0xffff0000, v211
	v_mul_f32_e32 v186, 0xbfb8aa3b, v186
	v_mul_f32_e32 v187, 0xbfb8aa3b, v187
	v_mul_f32_e32 v188, 0xbfb8aa3b, v188
	v_mul_f32_e32 v189, 0xbfb8aa3b, v189
	v_mul_f32_e32 v190, 0xbfb8aa3b, v190
	v_mul_f32_e32 v191, 0xbfb8aa3b, v191
	v_mul_f32_e32 v192, 0xbfb8aa3b, v192
	v_mul_f32_e32 v193, 0xbfb8aa3b, v193
	v_exp_f32_e32 v186, v186
	v_exp_f32_e32 v187, v187
	v_exp_f32_e32 v188, v188
	v_exp_f32_e32 v189, v189
	v_exp_f32_e32 v190, v190
	v_exp_f32_e32 v191, v191
	v_exp_f32_e32 v192, v192
	v_exp_f32_e32 v193, v193
	v_add_f32_e32 v186, 1.0, v186
	v_add_f32_e32 v187, 1.0, v187
	v_add_f32_e32 v188, 1.0, v188
	v_add_f32_e32 v189, 1.0, v189
	v_add_f32_e32 v190, 1.0, v190
	v_add_f32_e32 v191, 1.0, v191
	v_add_f32_e32 v192, 1.0, v192
	v_add_f32_e32 v193, 1.0, v193
	v_rcp_f32_e32 v186, v186
	v_rcp_f32_e32 v187, v187
	v_rcp_f32_e32 v188, v188
	v_rcp_f32_e32 v189, v189
	v_rcp_f32_e32 v190, v190
	v_rcp_f32_e32 v191, v191
	v_rcp_f32_e32 v192, v192
	v_rcp_f32_e32 v193, v193
	v_mov_b32_e32 v250, v72
	v_ashrrev_i32_e32 v251, 31, v250
	v_fma_f32 v73, v60, v186, v181
	v_fma_f32 v154, v61, v187, v182
	v_fma_f32 v155, v62, v188, v183
	v_fma_f32 v156, v63, v189, v184
	v_fma_f32 v157, v56, v190, v177
	v_fma_f32 v158, v57, v191, v178
	v_fma_f32 v159, v58, v192, v179
	v_fma_f32 v160, v59, v193, v180
	v_lshlrev_b64 v[248:249], 11, v[250:251]
	v_cvt_pk_bf16_f32 v208, v73, v154
	v_cvt_pk_bf16_f32 v209, v155, v156
	v_cvt_pk_bf16_f32 v210, v157, v158
	v_cvt_pk_bf16_f32 v211, v159, v160
	v_lshl_add_u64 v[248:249], v[70:71], 0, v[248:249]
	global_store_dwordx4 v[248:249], v[208:211], off
	v_lshlrev_b32_e32 v186, 16, v212
	v_and_b32_e32 v187, 0xffff0000, v212
	v_lshlrev_b32_e32 v188, 16, v213
	v_and_b32_e32 v189, 0xffff0000, v213
	v_lshlrev_b32_e32 v190, 16, v214
	v_and_b32_e32 v191, 0xffff0000, v214
	v_lshlrev_b32_e32 v192, 16, v215
	v_and_b32_e32 v193, 0xffff0000, v215
	v_mul_f32_e32 v186, 0xbfb8aa3b, v186
	v_mul_f32_e32 v187, 0xbfb8aa3b, v187
	v_mul_f32_e32 v188, 0xbfb8aa3b, v188
	v_mul_f32_e32 v189, 0xbfb8aa3b, v189
	v_mul_f32_e32 v190, 0xbfb8aa3b, v190
	v_mul_f32_e32 v191, 0xbfb8aa3b, v191
	v_mul_f32_e32 v192, 0xbfb8aa3b, v192
	v_mul_f32_e32 v193, 0xbfb8aa3b, v193
	v_exp_f32_e32 v186, v186
	v_exp_f32_e32 v187, v187
	v_exp_f32_e32 v188, v188
	v_exp_f32_e32 v189, v189
	v_exp_f32_e32 v190, v190
	v_exp_f32_e32 v191, v191
	v_exp_f32_e32 v192, v192
	v_exp_f32_e32 v193, v193
	v_add_f32_e32 v186, 1.0, v186
	v_add_f32_e32 v187, 1.0, v187
	v_add_f32_e32 v188, 1.0, v188
	v_add_f32_e32 v189, 1.0, v189
	v_add_f32_e32 v190, 1.0, v190
	v_add_f32_e32 v191, 1.0, v191
	v_add_f32_e32 v192, 1.0, v192
	v_add_f32_e32 v193, 1.0, v193
	v_rcp_f32_e32 v186, v186
	v_rcp_f32_e32 v187, v187
	v_rcp_f32_e32 v188, v188
	v_rcp_f32_e32 v189, v189
	v_rcp_f32_e32 v190, v190
	v_rcp_f32_e32 v191, v191
	v_rcp_f32_e32 v192, v192
	v_rcp_f32_e32 v193, v193
	v_or_b32_e32 v250, 16, v72
	v_ashrrev_i32_e32 v251, 31, v250
	v_fma_f32 v56, v52, v186, v173
	v_fma_f32 v57, v53, v187, v174
	v_fma_f32 v58, v54, v188, v175
	v_fma_f32 v59, v55, v189, v176
	v_fma_f32 v60, v48, v190, v169
	v_fma_f32 v61, v49, v191, v170
	v_fma_f32 v62, v50, v192, v171
	v_fma_f32 v63, v51, v193, v172
	v_lshlrev_b64 v[248:249], 11, v[250:251]
	v_cvt_pk_bf16_f32 v212, v56, v57
	v_cvt_pk_bf16_f32 v213, v58, v59
	v_cvt_pk_bf16_f32 v214, v60, v61
	v_cvt_pk_bf16_f32 v215, v62, v63
	v_lshl_add_u64 v[248:249], v[70:71], 0, v[248:249]
	global_store_dwordx4 v[248:249], v[212:215], off
	v_lshlrev_b32_e32 v186, 16, v216
	v_and_b32_e32 v187, 0xffff0000, v216
	v_lshlrev_b32_e32 v188, 16, v217
	v_and_b32_e32 v189, 0xffff0000, v217
	v_lshlrev_b32_e32 v190, 16, v218
	v_and_b32_e32 v191, 0xffff0000, v218
	v_lshlrev_b32_e32 v192, 16, v219
	v_and_b32_e32 v193, 0xffff0000, v219
	v_mul_f32_e32 v186, 0xbfb8aa3b, v186
	v_mul_f32_e32 v187, 0xbfb8aa3b, v187
	v_mul_f32_e32 v188, 0xbfb8aa3b, v188
	v_mul_f32_e32 v189, 0xbfb8aa3b, v189
	v_mul_f32_e32 v190, 0xbfb8aa3b, v190
	v_mul_f32_e32 v191, 0xbfb8aa3b, v191
	v_mul_f32_e32 v192, 0xbfb8aa3b, v192
	v_mul_f32_e32 v193, 0xbfb8aa3b, v193
	v_exp_f32_e32 v186, v186
	v_exp_f32_e32 v187, v187
	v_exp_f32_e32 v188, v188
	v_exp_f32_e32 v189, v189
	v_exp_f32_e32 v190, v190
	v_exp_f32_e32 v191, v191
	v_exp_f32_e32 v192, v192
	v_exp_f32_e32 v193, v193
	v_add_f32_e32 v186, 1.0, v186
	v_add_f32_e32 v187, 1.0, v187
	v_add_f32_e32 v188, 1.0, v188
	v_add_f32_e32 v189, 1.0, v189
	v_add_f32_e32 v190, 1.0, v190
	v_add_f32_e32 v191, 1.0, v191
	v_add_f32_e32 v192, 1.0, v192
	v_add_f32_e32 v193, 1.0, v193
	v_rcp_f32_e32 v186, v186
	v_rcp_f32_e32 v187, v187
	v_rcp_f32_e32 v188, v188
	v_rcp_f32_e32 v189, v189
	v_rcp_f32_e32 v190, v190
	v_rcp_f32_e32 v191, v191
	v_rcp_f32_e32 v192, v192
	v_rcp_f32_e32 v193, v193
	v_or_b32_e32 v250, 32, v72
	v_ashrrev_i32_e32 v251, 31, v250
	v_fma_f32 v48, v44, v186, v165
	v_fma_f32 v49, v45, v187, v166
	v_fma_f32 v50, v46, v188, v167
	v_fma_f32 v51, v47, v189, v168
	v_fma_f32 v52, v40, v190, v161
	v_fma_f32 v53, v41, v191, v162
	v_fma_f32 v54, v42, v192, v163
	v_fma_f32 v55, v43, v193, v164
	v_lshlrev_b64 v[248:249], 11, v[250:251]
	v_cvt_pk_bf16_f32 v216, v48, v49
	v_cvt_pk_bf16_f32 v217, v50, v51
	v_cvt_pk_bf16_f32 v218, v52, v53
	v_cvt_pk_bf16_f32 v219, v54, v55
	v_lshl_add_u64 v[248:249], v[70:71], 0, v[248:249]
	global_store_dwordx4 v[248:249], v[216:219], off
	v_lshlrev_b32_e32 v186, 16, v220
	v_and_b32_e32 v187, 0xffff0000, v220
	v_lshlrev_b32_e32 v188, 16, v221
	v_and_b32_e32 v189, 0xffff0000, v221
	v_lshlrev_b32_e32 v190, 16, v222
	v_and_b32_e32 v191, 0xffff0000, v222
	v_lshlrev_b32_e32 v192, 16, v223
	v_and_b32_e32 v193, 0xffff0000, v223
	v_mul_f32_e32 v186, 0xbfb8aa3b, v186
	v_mul_f32_e32 v187, 0xbfb8aa3b, v187
	v_mul_f32_e32 v188, 0xbfb8aa3b, v188
	v_mul_f32_e32 v189, 0xbfb8aa3b, v189
	v_mul_f32_e32 v190, 0xbfb8aa3b, v190
	v_mul_f32_e32 v191, 0xbfb8aa3b, v191
	v_mul_f32_e32 v192, 0xbfb8aa3b, v192
	v_mul_f32_e32 v193, 0xbfb8aa3b, v193
	v_exp_f32_e32 v186, v186
	v_exp_f32_e32 v187, v187
	v_exp_f32_e32 v188, v188
	v_exp_f32_e32 v189, v189
	v_exp_f32_e32 v190, v190
	v_exp_f32_e32 v191, v191
	v_exp_f32_e32 v192, v192
	v_exp_f32_e32 v193, v193
	v_add_f32_e32 v186, 1.0, v186
	v_add_f32_e32 v187, 1.0, v187
	v_add_f32_e32 v188, 1.0, v188
	v_add_f32_e32 v189, 1.0, v189
	v_add_f32_e32 v190, 1.0, v190
	v_add_f32_e32 v191, 1.0, v191
	v_add_f32_e32 v192, 1.0, v192
	v_add_f32_e32 v193, 1.0, v193
	v_rcp_f32_e32 v186, v186
	v_rcp_f32_e32 v187, v187
	v_rcp_f32_e32 v188, v188
	v_rcp_f32_e32 v189, v189
	v_rcp_f32_e32 v190, v190
	v_rcp_f32_e32 v191, v191
	v_rcp_f32_e32 v192, v192
	v_rcp_f32_e32 v193, v193
	v_or_b32_e32 v250, 48, v72
	v_ashrrev_i32_e32 v251, 31, v250
	v_fma_f32 v40, v36, v186, v150
	v_fma_f32 v41, v37, v187, v151
	v_fma_f32 v42, v38, v188, v152
	v_fma_f32 v43, v39, v189, v153
	v_fma_f32 v44, v32, v190, v146
	v_fma_f32 v45, v33, v191, v147
	v_fma_f32 v46, v34, v192, v148
	v_fma_f32 v47, v35, v193, v149
	v_lshlrev_b64 v[248:249], 11, v[250:251]
	v_cvt_pk_bf16_f32 v220, v40, v41
	v_cvt_pk_bf16_f32 v221, v42, v43
	v_cvt_pk_bf16_f32 v222, v44, v45
	v_cvt_pk_bf16_f32 v223, v46, v47
	v_lshl_add_u64 v[248:249], v[70:71], 0, v[248:249]
	global_store_dwordx4 v[248:249], v[220:223], off
	v_lshlrev_b32_e32 v186, 16, v224
	v_and_b32_e32 v187, 0xffff0000, v224
	v_lshlrev_b32_e32 v188, 16, v225
	v_and_b32_e32 v189, 0xffff0000, v225
	v_lshlrev_b32_e32 v190, 16, v226
	v_and_b32_e32 v191, 0xffff0000, v226
	v_lshlrev_b32_e32 v192, 16, v227
	v_and_b32_e32 v193, 0xffff0000, v227
	v_mul_f32_e32 v186, 0xbfb8aa3b, v186
	v_mul_f32_e32 v187, 0xbfb8aa3b, v187
	v_mul_f32_e32 v188, 0xbfb8aa3b, v188
	v_mul_f32_e32 v189, 0xbfb8aa3b, v189
	v_mul_f32_e32 v190, 0xbfb8aa3b, v190
	v_mul_f32_e32 v191, 0xbfb8aa3b, v191
	v_mul_f32_e32 v192, 0xbfb8aa3b, v192
	v_mul_f32_e32 v193, 0xbfb8aa3b, v193
	v_exp_f32_e32 v186, v186
	v_exp_f32_e32 v187, v187
	v_exp_f32_e32 v188, v188
	v_exp_f32_e32 v189, v189
	v_exp_f32_e32 v190, v190
	v_exp_f32_e32 v191, v191
	v_exp_f32_e32 v192, v192
	v_exp_f32_e32 v193, v193
	v_add_f32_e32 v186, 1.0, v186
	v_add_f32_e32 v187, 1.0, v187
	v_add_f32_e32 v188, 1.0, v188
	v_add_f32_e32 v189, 1.0, v189
	v_add_f32_e32 v190, 1.0, v190
	v_add_f32_e32 v191, 1.0, v191
	v_add_f32_e32 v192, 1.0, v192
	v_add_f32_e32 v193, 1.0, v193
	v_rcp_f32_e32 v186, v186
	v_rcp_f32_e32 v187, v187
	v_rcp_f32_e32 v188, v188
	v_rcp_f32_e32 v189, v189
	v_rcp_f32_e32 v190, v190
	v_rcp_f32_e32 v191, v191
	v_rcp_f32_e32 v192, v192
	v_rcp_f32_e32 v193, v193
	v_add_u32_e32 v250, 0x80, v72
	v_ashrrev_i32_e32 v251, 31, v250
	v_fma_f32 v32, v28, v186, v140
	v_fma_f32 v33, v29, v187, v141
	v_fma_f32 v34, v30, v188, v142
	v_fma_f32 v35, v31, v189, v143
	v_fma_f32 v36, v24, v190, v136
	v_fma_f32 v37, v25, v191, v137
	v_fma_f32 v38, v26, v192, v138
	v_fma_f32 v39, v27, v193, v139
	v_lshlrev_b64 v[248:249], 11, v[250:251]
	v_cvt_pk_bf16_f32 v224, v32, v33
	v_cvt_pk_bf16_f32 v225, v34, v35
	v_cvt_pk_bf16_f32 v226, v36, v37
	v_cvt_pk_bf16_f32 v227, v38, v39
	v_lshl_add_u64 v[248:249], v[70:71], 0, v[248:249]
	global_store_dwordx4 v[248:249], v[224:227], off
	v_lshlrev_b32_e32 v186, 16, v228
	v_and_b32_e32 v187, 0xffff0000, v228
	v_lshlrev_b32_e32 v188, 16, v229
	v_and_b32_e32 v189, 0xffff0000, v229
	v_lshlrev_b32_e32 v190, 16, v230
	v_and_b32_e32 v191, 0xffff0000, v230
	v_lshlrev_b32_e32 v192, 16, v231
	v_and_b32_e32 v193, 0xffff0000, v231
	v_mul_f32_e32 v186, 0xbfb8aa3b, v186
	v_mul_f32_e32 v187, 0xbfb8aa3b, v187
	v_mul_f32_e32 v188, 0xbfb8aa3b, v188
	v_mul_f32_e32 v189, 0xbfb8aa3b, v189
	v_mul_f32_e32 v190, 0xbfb8aa3b, v190
	v_mul_f32_e32 v191, 0xbfb8aa3b, v191
	v_mul_f32_e32 v192, 0xbfb8aa3b, v192
	v_mul_f32_e32 v193, 0xbfb8aa3b, v193
	v_exp_f32_e32 v186, v186
	v_exp_f32_e32 v187, v187
	v_exp_f32_e32 v188, v188
	v_exp_f32_e32 v189, v189
	v_exp_f32_e32 v190, v190
	v_exp_f32_e32 v191, v191
	v_exp_f32_e32 v192, v192
	v_exp_f32_e32 v193, v193
	v_add_f32_e32 v186, 1.0, v186
	v_add_f32_e32 v187, 1.0, v187
	v_add_f32_e32 v188, 1.0, v188
	v_add_f32_e32 v189, 1.0, v189
	v_add_f32_e32 v190, 1.0, v190
	v_add_f32_e32 v191, 1.0, v191
	v_add_f32_e32 v192, 1.0, v192
	v_add_f32_e32 v193, 1.0, v193
	v_rcp_f32_e32 v186, v186
	v_rcp_f32_e32 v187, v187
	v_rcp_f32_e32 v188, v188
	v_rcp_f32_e32 v189, v189
	v_rcp_f32_e32 v190, v190
	v_rcp_f32_e32 v191, v191
	v_rcp_f32_e32 v192, v192
	v_rcp_f32_e32 v193, v193
	v_add_u32_e32 v250, 0x90, v72
	v_ashrrev_i32_e32 v251, 31, v250
	v_fma_f32 v24, v20, v186, v132
	v_fma_f32 v25, v21, v187, v133
	v_fma_f32 v26, v22, v188, v134
	v_fma_f32 v27, v23, v189, v135
	v_fma_f32 v28, v16, v190, v128
	v_fma_f32 v29, v17, v191, v129
	v_fma_f32 v30, v18, v192, v130
	v_fma_f32 v31, v19, v193, v131
	v_lshlrev_b64 v[248:249], 11, v[250:251]
	v_cvt_pk_bf16_f32 v228, v24, v25
	v_cvt_pk_bf16_f32 v229, v26, v27
	v_cvt_pk_bf16_f32 v230, v28, v29
	v_cvt_pk_bf16_f32 v231, v30, v31
	v_lshl_add_u64 v[248:249], v[70:71], 0, v[248:249]
	global_store_dwordx4 v[248:249], v[228:231], off
	v_lshlrev_b32_e32 v186, 16, v232
	v_and_b32_e32 v187, 0xffff0000, v232
	v_lshlrev_b32_e32 v188, 16, v233
	v_and_b32_e32 v189, 0xffff0000, v233
	v_lshlrev_b32_e32 v190, 16, v234
	v_and_b32_e32 v191, 0xffff0000, v234
	v_lshlrev_b32_e32 v192, 16, v235
	v_and_b32_e32 v193, 0xffff0000, v235
	v_mul_f32_e32 v186, 0xbfb8aa3b, v186
	v_mul_f32_e32 v187, 0xbfb8aa3b, v187
	v_mul_f32_e32 v188, 0xbfb8aa3b, v188
	v_mul_f32_e32 v189, 0xbfb8aa3b, v189
	v_mul_f32_e32 v190, 0xbfb8aa3b, v190
	v_mul_f32_e32 v191, 0xbfb8aa3b, v191
	v_mul_f32_e32 v192, 0xbfb8aa3b, v192
	v_mul_f32_e32 v193, 0xbfb8aa3b, v193
	v_exp_f32_e32 v186, v186
	v_exp_f32_e32 v187, v187
	v_exp_f32_e32 v188, v188
	v_exp_f32_e32 v189, v189
	v_exp_f32_e32 v190, v190
	v_exp_f32_e32 v191, v191
	v_exp_f32_e32 v192, v192
	v_exp_f32_e32 v193, v193
	v_add_f32_e32 v186, 1.0, v186
	v_add_f32_e32 v187, 1.0, v187
	v_add_f32_e32 v188, 1.0, v188
	v_add_f32_e32 v189, 1.0, v189
	v_add_f32_e32 v190, 1.0, v190
	v_add_f32_e32 v191, 1.0, v191
	v_add_f32_e32 v192, 1.0, v192
	v_add_f32_e32 v193, 1.0, v193
	v_rcp_f32_e32 v186, v186
	v_rcp_f32_e32 v187, v187
	v_rcp_f32_e32 v188, v188
	v_rcp_f32_e32 v189, v189
	v_rcp_f32_e32 v190, v190
	v_rcp_f32_e32 v191, v191
	v_rcp_f32_e32 v192, v192
	v_rcp_f32_e32 v193, v193
	v_add_u32_e32 v250, 0xa0, v72
	v_ashrrev_i32_e32 v251, 31, v250
	v_fma_f32 v16, v12, v186, v124
	v_fma_f32 v17, v13, v187, v125
	v_fma_f32 v18, v14, v188, v126
	v_fma_f32 v19, v15, v189, v127
	v_fma_f32 v20, v8, v190, v120
	v_fma_f32 v21, v9, v191, v121
	v_fma_f32 v22, v10, v192, v122
	v_fma_f32 v23, v11, v193, v123
	v_lshlrev_b64 v[248:249], 11, v[250:251]
	v_cvt_pk_bf16_f32 v232, v16, v17
	v_cvt_pk_bf16_f32 v233, v18, v19
	v_cvt_pk_bf16_f32 v234, v20, v21
	v_cvt_pk_bf16_f32 v235, v22, v23
	v_lshl_add_u64 v[248:249], v[70:71], 0, v[248:249]
	global_store_dwordx4 v[248:249], v[232:235], off
	v_lshlrev_b32_e32 v186, 16, v240
	v_and_b32_e32 v187, 0xffff0000, v240
	v_lshlrev_b32_e32 v188, 16, v241
	v_and_b32_e32 v189, 0xffff0000, v241
	v_lshlrev_b32_e32 v190, 16, v242
	v_and_b32_e32 v191, 0xffff0000, v242
	v_lshlrev_b32_e32 v192, 16, v243
	v_and_b32_e32 v193, 0xffff0000, v243
	v_mul_f32_e32 v186, 0xbfb8aa3b, v186
	v_mul_f32_e32 v187, 0xbfb8aa3b, v187
	v_mul_f32_e32 v188, 0xbfb8aa3b, v188
	v_mul_f32_e32 v189, 0xbfb8aa3b, v189
	v_mul_f32_e32 v190, 0xbfb8aa3b, v190
	v_mul_f32_e32 v191, 0xbfb8aa3b, v191
	v_mul_f32_e32 v192, 0xbfb8aa3b, v192
	v_mul_f32_e32 v193, 0xbfb8aa3b, v193
	v_exp_f32_e32 v186, v186
	v_exp_f32_e32 v187, v187
	v_exp_f32_e32 v188, v188
	v_exp_f32_e32 v189, v189
	v_exp_f32_e32 v190, v190
	v_exp_f32_e32 v191, v191
	v_exp_f32_e32 v192, v192
	v_exp_f32_e32 v193, v193
	v_add_f32_e32 v186, 1.0, v186
	v_add_f32_e32 v187, 1.0, v187
	v_add_f32_e32 v188, 1.0, v188
	v_add_f32_e32 v189, 1.0, v189
	v_add_f32_e32 v190, 1.0, v190
	v_add_f32_e32 v191, 1.0, v191
	v_add_f32_e32 v192, 1.0, v192
	v_add_f32_e32 v193, 1.0, v193
	v_rcp_f32_e32 v186, v186
	v_rcp_f32_e32 v187, v187
	v_rcp_f32_e32 v188, v188
	v_rcp_f32_e32 v189, v189
	v_rcp_f32_e32 v190, v190
	v_rcp_f32_e32 v191, v191
	v_rcp_f32_e32 v192, v192
	v_rcp_f32_e32 v193, v193
	v_add_u32_e32 v250, 0xb0, v72
	v_ashrrev_i32_e32 v251, 31, v250
	v_fma_f32 v8, v4, v186, v116
	v_fma_f32 v9, v5, v187, v117
	v_fma_f32 v10, v6, v188, v118
	v_fma_f32 v11, v7, v189, v119
	v_fma_f32 v12, v0, v190, v112
	v_fma_f32 v13, v1, v191, v113
	v_fma_f32 v14, v2, v192, v114
	v_fma_f32 v15, v3, v193, v115
	v_lshlrev_b64 v[248:249], 11, v[250:251]
	v_cvt_pk_bf16_f32 v240, v8, v9
	v_cvt_pk_bf16_f32 v241, v10, v11
	v_cvt_pk_bf16_f32 v242, v12, v13
	v_cvt_pk_bf16_f32 v243, v14, v15
	v_lshl_add_u64 v[248:249], v[70:71], 0, v[248:249]
	global_store_dwordx4 v[248:249], v[240:243], off
	s_branch .LBB0_174
